# P14 EpiRes epilogue: all 16 hb loads hoisted to epilogue top, counted vmcnt
# speedup vs baseline: 1.0151x; 1.0151x over previous
.LBB0_1837:
	v_lshl_add_u32 v148, s24, 8, v1
	v_ashrrev_i32_e32 v149, 31, v148
	v_lshl_or_b32 v146, s26, 8, v151
	v_lshlrev_b64 v[156:157], 11, v[148:149]
	v_ashrrev_i32_e32 v147, 31, v146
	v_lshl_add_u64 v[156:157], s[92:93], 0, v[156:157]
	v_lshl_add_u64 v[160:161], v[146:147], 1, v[156:157]
	global_load_dwordx4 v[170:173], v[160:161], off
	global_load_dwordx4 v[174:177], v[160:161], off offset:256
	v_or_b32_e32 v178, 16, v148
	v_ashrrev_i32_e32 v179, 31, v178
	v_lshlrev_b64 v[246:247], 11, v[178:179]
	v_lshl_add_u64 v[246:247], s[92:93], 0, v[246:247]
	v_lshl_add_u64 v[252:253], v[146:147], 1, v[246:247]
	global_load_dwordx4 v[182:185], v[252:253], off
	global_load_dwordx4 v[186:189], v[252:253], off offset:256
	v_or_b32_e32 v254, 32, v148
	v_ashrrev_i32_e32 v255, 31, v254
	v_lshlrev_b64 v[178:179], 11, v[254:255]
	v_lshl_add_u64 v[178:179], s[92:93], 0, v[178:179]
	v_lshl_add_u64 v[246:247], v[146:147], 1, v[178:179]
	global_load_dwordx4 v[190:193], v[246:247], off
	global_load_dwordx4 v[194:197], v[246:247], off offset:256
	v_or_b32_e32 v252, 48, v148
	v_ashrrev_i32_e32 v253, 31, v252
	v_lshlrev_b64 v[254:255], 11, v[252:253]
	v_lshl_add_u64 v[254:255], s[92:93], 0, v[254:255]
	v_lshl_add_u64 v[178:179], v[146:147], 1, v[254:255]
	global_load_dwordx4 v[198:201], v[178:179], off
	global_load_dwordx4 v[202:205], v[178:179], off offset:256
	v_add_u32_e32 v246, 0x80, v148
	v_ashrrev_i32_e32 v247, 31, v246
	v_lshlrev_b64 v[252:253], 11, v[246:247]
	v_lshl_add_u64 v[252:253], s[92:93], 0, v[252:253]
	v_lshl_add_u64 v[254:255], v[146:147], 1, v[252:253]
	global_load_dwordx4 v[206:209], v[254:255], off
	global_load_dwordx4 v[210:213], v[254:255], off offset:256
	v_add_u32_e32 v178, 0x90, v148
	v_ashrrev_i32_e32 v179, 31, v178
	v_lshlrev_b64 v[246:247], 11, v[178:179]
	v_lshl_add_u64 v[246:247], s[92:93], 0, v[246:247]
	v_lshl_add_u64 v[252:253], v[146:147], 1, v[246:247]
	global_load_dwordx4 v[214:217], v[252:253], off
	global_load_dwordx4 v[228:231], v[252:253], off offset:256
	v_add_u32_e32 v254, 0xa0, v148
	v_ashrrev_i32_e32 v255, 31, v254
	v_lshlrev_b64 v[178:179], 11, v[254:255]
	v_lshl_add_u64 v[178:179], s[92:93], 0, v[178:179]
	v_lshl_add_u64 v[246:247], v[146:147], 1, v[178:179]
	global_load_dwordx4 v[232:235], v[246:247], off
	global_load_dwordx4 v[236:239], v[246:247], off offset:256
	v_add_u32_e32 v252, 0xb0, v148
	v_ashrrev_i32_e32 v253, 31, v252
	v_lshlrev_b64 v[254:255], 11, v[252:253]
	v_lshl_add_u64 v[254:255], s[92:93], 0, v[254:255]
	v_lshl_add_u64 v[178:179], v[146:147], 1, v[254:255]
	global_load_dwordx4 v[240:243], v[178:179], off
	global_load_dwordx4 v[248:251], v[178:179], off offset:256
	s_nop 0
	v_xor_b32_e32 v168, 32, v155
	s_waitcnt vmcnt(15)
	v_lshlrev_b32_e32 v162, 16, v170
	v_and_b32_e32 v163, 0xffff0000, v170
	v_lshlrev_b32_e32 v156, 16, v171
	v_and_b32_e32 v157, 0xffff0000, v171
	v_lshlrev_b32_e32 v164, 16, v172
	v_and_b32_e32 v165, 0xffff0000, v172
	v_lshlrev_b32_e32 v158, 16, v173
	v_and_b32_e32 v159, 0xffff0000, v173
	v_pk_add_f32 v[128:129], v[128:129], v[156:157]
	v_pk_add_f32 v[162:163], v[126:127], v[162:163]
	v_pk_add_f32 v[166:167], v[124:125], v[158:159]
	v_pk_add_f32 v[164:165], v[122:123], v[164:165]
	v_cvt_pk_bf16_f32 v124, v162, v163
	v_cvt_pk_bf16_f32 v125, v128, v129
	v_mul_f32_e32 v169, v163, v163
	v_cvt_pk_bf16_f32 v126, v164, v165
	v_cvt_pk_bf16_f32 v127, v166, v167
	s_nop 0
	v_fmac_f32_e32 v169, v162, v162
	v_fmac_f32_e32 v169, v128, v128
	v_fmac_f32_e32 v169, v129, v129
	v_and_b32_e32 v123, 64, v155
	v_fmac_f32_e32 v169, v164, v164
	v_xor_b32_e32 v122, 16, v155
	v_add_u32_e32 v123, 64, v123
	v_fmac_f32_e32 v169, v165, v165
	v_cmp_lt_i32_e32 vcc, v122, v123
	v_fmac_f32_e32 v169, v166, v166
	v_fmac_f32_e32 v169, v167, v167
	v_cndmask_b32_e32 v122, v155, v122, vcc
	v_lshlrev_b32_e32 v122, 2, v122
	v_cmp_lt_i32_e32 vcc, v168, v123
	global_store_dwordx4 v[160:161], v[124:127], off
	s_waitcnt vmcnt(15)
	v_lshlrev_b32_e32 v128, 16, v174
	v_and_b32_e32 v129, 0xffff0000, v174
	v_lshlrev_b32_e32 v156, 16, v175
	v_and_b32_e32 v157, 0xffff0000, v175
	v_lshlrev_b32_e32 v162, 16, v176
	v_and_b32_e32 v163, 0xffff0000, v176
	v_pk_add_f32 v[118:119], v[118:119], v[128:129]
	v_pk_add_f32 v[120:121], v[120:121], v[156:157]
	v_pk_add_f32 v[156:157], v[114:115], v[162:163]
	v_mul_f32_e32 v114, v119, v119
	v_fmac_f32_e32 v114, v118, v118
	v_fmac_f32_e32 v114, v120, v120
	v_fmac_f32_e32 v114, v121, v121
	v_lshlrev_b32_e32 v158, 16, v177
	v_and_b32_e32 v159, 0xffff0000, v177
	v_fmac_f32_e32 v114, v156, v156
	v_pk_add_f32 v[128:129], v[116:117], v[158:159]
	v_fmac_f32_e32 v114, v157, v157
	v_fmac_f32_e32 v114, v128, v128
	v_fmac_f32_e32 v114, v129, v129
	v_add_f32_e32 v114, v169, v114
	ds_bpermute_b32 v115, v122, v114
	v_cndmask_b32_e32 v116, v155, v168, vcc
	v_lshlrev_b32_e32 v116, 2, v116
	v_cvt_pk_bf16_f32 v118, v118, v119
	v_cvt_pk_bf16_f32 v119, v120, v121
	s_waitcnt lgkmcnt(0)
	v_add_f32_e32 v114, v114, v115
	ds_bpermute_b32 v115, v116, v114
	v_cvt_pk_bf16_f32 v120, v156, v157
	v_cvt_pk_bf16_f32 v121, v128, v129
	global_store_dwordx4 v[160:161], v[118:121], off offset:256
	s_and_saveexec_b64 s[24:25], s[2:3]
	s_cbranch_execz .LBB0_1839
	v_lshl_add_u64 v[118:119], v[148:149], 2, s[10:11]
	s_waitcnt lgkmcnt(0)
	v_add_f32_e32 v114, v114, v115
	global_atomic_add_f32 v[118:119], v114, off
.LBB0_1839:
	s_or_b64 exec, exec, s[24:25]
	v_or_b32_e32 v114, 16, v148
	s_waitcnt lgkmcnt(0)
	v_ashrrev_i32_e32 v115, 31, v114
	v_lshlrev_b64 v[118:119], 11, v[114:115]
	v_lshl_add_u64 v[118:119], s[92:93], 0, v[118:119]
	v_lshl_add_u64 v[124:125], v[146:147], 1, v[118:119]
	s_nop 0
	s_waitcnt vmcnt(15)
	v_lshlrev_b32_e32 v126, 16, v182
	v_and_b32_e32 v127, 0xffff0000, v182
	v_lshlrev_b32_e32 v118, 16, v183
	v_and_b32_e32 v119, 0xffff0000, v183
	v_lshlrev_b32_e32 v128, 16, v184
	v_and_b32_e32 v129, 0xffff0000, v184
	v_lshlrev_b32_e32 v120, 16, v185
	v_and_b32_e32 v121, 0xffff0000, v185
	v_pk_add_f32 v[118:119], v[112:113], v[118:119]
	v_pk_add_f32 v[126:127], v[110:111], v[126:127]
	v_pk_add_f32 v[120:121], v[108:109], v[120:121]
	v_pk_add_f32 v[128:129], v[106:107], v[128:129]
	v_cvt_pk_bf16_f32 v106, v126, v127
	v_cvt_pk_bf16_f32 v107, v118, v119
	v_mul_f32_e32 v117, v127, v127
	v_cvt_pk_bf16_f32 v108, v128, v129
	v_cvt_pk_bf16_f32 v109, v120, v121
	s_nop 0
	v_fmac_f32_e32 v117, v126, v126
	v_fmac_f32_e32 v117, v118, v118
	v_fmac_f32_e32 v117, v119, v119
	v_fmac_f32_e32 v117, v128, v128
	v_fmac_f32_e32 v117, v129, v129
	v_fmac_f32_e32 v117, v120, v120
	v_fmac_f32_e32 v117, v121, v121
	global_store_dwordx4 v[124:125], v[106:109], off
	s_waitcnt vmcnt(15)
	v_lshlrev_b32_e32 v118, 16, v186
	v_and_b32_e32 v119, 0xffff0000, v186
	v_lshlrev_b32_e32 v110, 16, v187
	v_and_b32_e32 v111, 0xffff0000, v187
	v_lshlrev_b32_e32 v120, 16, v188
	v_and_b32_e32 v121, 0xffff0000, v188
	v_lshlrev_b32_e32 v112, 16, v189
	v_and_b32_e32 v113, 0xffff0000, v189
	v_pk_add_f32 v[102:103], v[102:103], v[118:119]
	v_pk_add_f32 v[104:105], v[104:105], v[110:111]
	v_pk_add_f32 v[110:111], v[100:101], v[112:113]
	v_pk_add_f32 v[112:113], v[98:99], v[120:121]
	v_mul_f32_e32 v98, v103, v103
	v_fmac_f32_e32 v98, v102, v102
	v_fmac_f32_e32 v98, v104, v104
	v_fmac_f32_e32 v98, v105, v105
	v_fmac_f32_e32 v98, v112, v112
	v_fmac_f32_e32 v98, v113, v113
	v_fmac_f32_e32 v98, v110, v110
	v_fmac_f32_e32 v98, v111, v111
	v_add_f32_e32 v98, v117, v98
	ds_bpermute_b32 v99, v122, v98
	v_cvt_pk_bf16_f32 v100, v102, v103
	v_cvt_pk_bf16_f32 v101, v104, v105
	v_cvt_pk_bf16_f32 v102, v112, v113
	v_cvt_pk_bf16_f32 v103, v110, v111
	s_waitcnt lgkmcnt(0)
	v_add_f32_e32 v98, v98, v99
	ds_bpermute_b32 v99, v116, v98
	global_store_dwordx4 v[124:125], v[100:103], off offset:256
	s_and_saveexec_b64 s[24:25], s[2:3]
	s_cbranch_execz .LBB0_1841
	v_lshl_add_u64 v[100:101], v[114:115], 2, s[10:11]
	s_waitcnt lgkmcnt(0)
	v_add_f32_e32 v98, v98, v99
	global_atomic_add_f32 v[100:101], v98, off
.LBB0_1841:
	s_or_b64 exec, exec, s[24:25]
	v_or_b32_e32 v98, 32, v148
	s_waitcnt lgkmcnt(0)
	v_ashrrev_i32_e32 v99, 31, v98
	v_lshlrev_b64 v[100:101], 11, v[98:99]
	v_lshl_add_u64 v[100:101], s[92:93], 0, v[100:101]
	v_lshl_add_u64 v[104:105], v[146:147], 1, v[100:101]
	s_nop 0
	s_waitcnt vmcnt(15)
	v_lshlrev_b32_e32 v106, 16, v190
	v_and_b32_e32 v107, 0xffff0000, v190
	v_lshlrev_b32_e32 v100, 16, v191
	v_and_b32_e32 v101, 0xffff0000, v191
	v_lshlrev_b32_e32 v108, 16, v192
	v_and_b32_e32 v109, 0xffff0000, v192
	v_lshlrev_b32_e32 v102, 16, v193
	v_and_b32_e32 v103, 0xffff0000, v193
	v_pk_add_f32 v[100:101], v[96:97], v[100:101]
	v_pk_add_f32 v[106:107], v[94:95], v[106:107]
	v_pk_add_f32 v[102:103], v[92:93], v[102:103]
	v_pk_add_f32 v[108:109], v[90:91], v[108:109]
	v_cvt_pk_bf16_f32 v90, v106, v107
	v_cvt_pk_bf16_f32 v91, v100, v101
	v_mul_f32_e32 v107, v107, v107
	v_cvt_pk_bf16_f32 v92, v108, v109
	v_cvt_pk_bf16_f32 v93, v102, v103
	s_nop 0
	v_fmac_f32_e32 v107, v106, v106
	v_fmac_f32_e32 v107, v100, v100
	v_fmac_f32_e32 v107, v101, v101
	v_fmac_f32_e32 v107, v108, v108
	v_fmac_f32_e32 v107, v109, v109
	v_fmac_f32_e32 v107, v102, v102
	v_fmac_f32_e32 v107, v103, v103
	global_store_dwordx4 v[104:105], v[90:93], off
	s_waitcnt vmcnt(15)
	v_lshlrev_b32_e32 v100, 16, v194
	v_and_b32_e32 v101, 0xffff0000, v194
	v_lshlrev_b32_e32 v94, 16, v195
	v_and_b32_e32 v95, 0xffff0000, v195
	v_lshlrev_b32_e32 v102, 16, v196
	v_and_b32_e32 v103, 0xffff0000, v196
	v_lshlrev_b32_e32 v96, 16, v197
	v_and_b32_e32 v97, 0xffff0000, v197
	v_pk_add_f32 v[86:87], v[86:87], v[100:101]
	v_pk_add_f32 v[88:89], v[88:89], v[94:95]
	v_pk_add_f32 v[94:95], v[84:85], v[96:97]
	v_pk_add_f32 v[96:97], v[82:83], v[102:103]
	v_mul_f32_e32 v82, v87, v87
	v_fmac_f32_e32 v82, v86, v86
	v_fmac_f32_e32 v82, v88, v88
	v_fmac_f32_e32 v82, v89, v89
	v_fmac_f32_e32 v82, v96, v96
	v_fmac_f32_e32 v82, v97, v97
	v_fmac_f32_e32 v82, v94, v94
	v_fmac_f32_e32 v82, v95, v95
	v_add_f32_e32 v82, v107, v82
	ds_bpermute_b32 v83, v122, v82
	v_cvt_pk_bf16_f32 v84, v86, v87
	v_cvt_pk_bf16_f32 v85, v88, v89
	v_cvt_pk_bf16_f32 v86, v96, v97
	v_cvt_pk_bf16_f32 v87, v94, v95
	s_waitcnt lgkmcnt(0)
	v_add_f32_e32 v82, v82, v83
	ds_bpermute_b32 v83, v116, v82
	global_store_dwordx4 v[104:105], v[84:87], off offset:256
	s_and_saveexec_b64 s[24:25], s[2:3]
	s_cbranch_execz .LBB0_1843
	v_lshl_add_u64 v[84:85], v[98:99], 2, s[10:11]
	s_waitcnt lgkmcnt(0)
	v_add_f32_e32 v82, v82, v83
	global_atomic_add_f32 v[84:85], v82, off
.LBB0_1843:
	s_or_b64 exec, exec, s[24:25]
	v_or_b32_e32 v82, 48, v148
	s_waitcnt lgkmcnt(0)
	v_ashrrev_i32_e32 v83, 31, v82
	v_lshlrev_b64 v[84:85], 11, v[82:83]
	v_lshl_add_u64 v[84:85], s[92:93], 0, v[84:85]
	v_lshl_add_u64 v[88:89], v[146:147], 1, v[84:85]
	s_nop 0
	s_waitcnt vmcnt(15)
	v_lshlrev_b32_e32 v90, 16, v198
	v_and_b32_e32 v91, 0xffff0000, v198
	v_lshlrev_b32_e32 v84, 16, v199
	v_and_b32_e32 v85, 0xffff0000, v199
	v_lshlrev_b32_e32 v92, 16, v200
	v_and_b32_e32 v93, 0xffff0000, v200
	v_lshlrev_b32_e32 v86, 16, v201
	v_and_b32_e32 v87, 0xffff0000, v201
	v_pk_add_f32 v[84:85], v[80:81], v[84:85]
	v_pk_add_f32 v[90:91], v[78:79], v[90:91]
	v_pk_add_f32 v[86:87], v[76:77], v[86:87]
	v_pk_add_f32 v[92:93], v[74:75], v[92:93]
	v_cvt_pk_bf16_f32 v74, v90, v91
	v_cvt_pk_bf16_f32 v75, v84, v85
	v_mul_f32_e32 v91, v91, v91
	v_cvt_pk_bf16_f32 v76, v92, v93
	v_cvt_pk_bf16_f32 v77, v86, v87
	s_nop 0
	v_fmac_f32_e32 v91, v90, v90
	v_fmac_f32_e32 v91, v84, v84
	v_fmac_f32_e32 v91, v85, v85
	v_fmac_f32_e32 v91, v92, v92
	v_fmac_f32_e32 v91, v93, v93
	v_fmac_f32_e32 v91, v86, v86
	v_fmac_f32_e32 v91, v87, v87
	global_store_dwordx4 v[88:89], v[74:77], off
	s_waitcnt vmcnt(15)
	v_lshlrev_b32_e32 v84, 16, v202
	v_and_b32_e32 v85, 0xffff0000, v202
	v_lshlrev_b32_e32 v78, 16, v203
	v_and_b32_e32 v79, 0xffff0000, v203
	v_lshlrev_b32_e32 v86, 16, v204
	v_and_b32_e32 v87, 0xffff0000, v204
	v_lshlrev_b32_e32 v80, 16, v205
	v_and_b32_e32 v81, 0xffff0000, v205
	v_pk_add_f32 v[70:71], v[70:71], v[84:85]
	v_pk_add_f32 v[72:73], v[72:73], v[78:79]
	v_pk_add_f32 v[78:79], v[68:69], v[80:81]
	v_pk_add_f32 v[80:81], v[66:67], v[86:87]
	v_mul_f32_e32 v66, v71, v71
	v_fmac_f32_e32 v66, v70, v70
	v_fmac_f32_e32 v66, v72, v72
	v_fmac_f32_e32 v66, v73, v73
	v_fmac_f32_e32 v66, v80, v80
	v_fmac_f32_e32 v66, v81, v81
	v_fmac_f32_e32 v66, v78, v78
	v_fmac_f32_e32 v66, v79, v79
	v_add_f32_e32 v66, v91, v66
	ds_bpermute_b32 v67, v122, v66
	v_cvt_pk_bf16_f32 v68, v70, v71
	v_cvt_pk_bf16_f32 v69, v72, v73
	v_cvt_pk_bf16_f32 v70, v80, v81
	v_cvt_pk_bf16_f32 v71, v78, v79
	s_waitcnt lgkmcnt(0)
	v_add_f32_e32 v66, v66, v67
	ds_bpermute_b32 v67, v116, v66
	global_store_dwordx4 v[88:89], v[68:71], off offset:256
	s_and_saveexec_b64 s[24:25], s[2:3]
	s_cbranch_execz .LBB0_1845
	v_lshl_add_u64 v[68:69], v[82:83], 2, s[10:11]
	s_waitcnt lgkmcnt(0)
	v_add_f32_e32 v66, v66, v67
	global_atomic_add_f32 v[68:69], v66, off
.LBB0_1845:
	s_or_b64 exec, exec, s[24:25]
	v_add_u32_e32 v66, 0x80, v148
	s_waitcnt lgkmcnt(0)
	v_ashrrev_i32_e32 v67, 31, v66
	v_lshlrev_b64 v[68:69], 11, v[66:67]
	v_lshl_add_u64 v[68:69], s[92:93], 0, v[68:69]
	v_lshl_add_u64 v[72:73], v[146:147], 1, v[68:69]
	s_nop 0
	s_waitcnt vmcnt(15)
	v_lshlrev_b32_e32 v74, 16, v206
	v_and_b32_e32 v75, 0xffff0000, v206
	v_lshlrev_b32_e32 v68, 16, v207
	v_and_b32_e32 v69, 0xffff0000, v207
	v_lshlrev_b32_e32 v76, 16, v208
	v_and_b32_e32 v77, 0xffff0000, v208
	v_lshlrev_b32_e32 v70, 16, v209
	v_and_b32_e32 v71, 0xffff0000, v209
	v_pk_add_f32 v[68:69], v[64:65], v[68:69]
	v_pk_add_f32 v[74:75], v[62:63], v[74:75]
	v_pk_add_f32 v[70:71], v[60:61], v[70:71]
	v_pk_add_f32 v[76:77], v[58:59], v[76:77]
	v_cvt_pk_bf16_f32 v58, v74, v75
	v_cvt_pk_bf16_f32 v59, v68, v69
	v_mul_f32_e32 v75, v75, v75
	v_cvt_pk_bf16_f32 v60, v76, v77
	v_cvt_pk_bf16_f32 v61, v70, v71
	s_nop 0
	v_fmac_f32_e32 v75, v74, v74
	v_fmac_f32_e32 v75, v68, v68
	v_fmac_f32_e32 v75, v69, v69
	v_fmac_f32_e32 v75, v76, v76
	v_fmac_f32_e32 v75, v77, v77
	v_fmac_f32_e32 v75, v70, v70
	v_fmac_f32_e32 v75, v71, v71
	global_store_dwordx4 v[72:73], v[58:61], off
	s_waitcnt vmcnt(15)
	v_lshlrev_b32_e32 v68, 16, v210
	v_and_b32_e32 v69, 0xffff0000, v210
	v_lshlrev_b32_e32 v62, 16, v211
	v_and_b32_e32 v63, 0xffff0000, v211
	v_lshlrev_b32_e32 v70, 16, v212
	v_and_b32_e32 v71, 0xffff0000, v212
	v_lshlrev_b32_e32 v64, 16, v213
	v_and_b32_e32 v65, 0xffff0000, v213
	v_pk_add_f32 v[54:55], v[54:55], v[68:69]
	v_pk_add_f32 v[56:57], v[56:57], v[62:63]
	v_pk_add_f32 v[62:63], v[52:53], v[64:65]
	v_pk_add_f32 v[64:65], v[50:51], v[70:71]
	v_mul_f32_e32 v50, v55, v55
	v_fmac_f32_e32 v50, v54, v54
	v_fmac_f32_e32 v50, v56, v56
	v_fmac_f32_e32 v50, v57, v57
	v_fmac_f32_e32 v50, v64, v64
	v_fmac_f32_e32 v50, v65, v65
	v_fmac_f32_e32 v50, v62, v62
	v_fmac_f32_e32 v50, v63, v63
	v_add_f32_e32 v50, v75, v50
	ds_bpermute_b32 v51, v122, v50
	v_cvt_pk_bf16_f32 v52, v54, v55
	v_cvt_pk_bf16_f32 v53, v56, v57
	v_cvt_pk_bf16_f32 v54, v64, v65
	v_cvt_pk_bf16_f32 v55, v62, v63
	s_waitcnt lgkmcnt(0)
	v_add_f32_e32 v50, v50, v51
	ds_bpermute_b32 v51, v116, v50
	global_store_dwordx4 v[72:73], v[52:55], off offset:256
	s_and_saveexec_b64 s[24:25], s[2:3]
	s_cbranch_execz .LBB0_1847
	v_lshl_add_u64 v[52:53], v[66:67], 2, s[10:11]
	s_waitcnt lgkmcnt(0)
	v_add_f32_e32 v50, v50, v51
	global_atomic_add_f32 v[52:53], v50, off
.LBB0_1847:
	s_or_b64 exec, exec, s[24:25]
	v_add_u32_e32 v50, 0x90, v148
	s_waitcnt lgkmcnt(0)
	v_ashrrev_i32_e32 v51, 31, v50
	v_lshlrev_b64 v[52:53], 11, v[50:51]
	v_lshl_add_u64 v[52:53], s[92:93], 0, v[52:53]
	v_lshl_add_u64 v[56:57], v[146:147], 1, v[52:53]
	s_nop 0
	s_waitcnt vmcnt(15)
	v_lshlrev_b32_e32 v58, 16, v214
	v_and_b32_e32 v59, 0xffff0000, v214
	v_lshlrev_b32_e32 v52, 16, v215
	v_and_b32_e32 v53, 0xffff0000, v215
	v_lshlrev_b32_e32 v60, 16, v216
	v_and_b32_e32 v61, 0xffff0000, v216
	v_lshlrev_b32_e32 v54, 16, v217
	v_and_b32_e32 v55, 0xffff0000, v217
	v_pk_add_f32 v[52:53], v[48:49], v[52:53]
	v_pk_add_f32 v[58:59], v[46:47], v[58:59]
	v_pk_add_f32 v[54:55], v[44:45], v[54:55]
	v_pk_add_f32 v[60:61], v[42:43], v[60:61]
	v_cvt_pk_bf16_f32 v42, v58, v59
	v_cvt_pk_bf16_f32 v43, v52, v53
	v_mul_f32_e32 v59, v59, v59
	v_cvt_pk_bf16_f32 v44, v60, v61
	v_cvt_pk_bf16_f32 v45, v54, v55
	s_nop 0
	v_fmac_f32_e32 v59, v58, v58
	v_fmac_f32_e32 v59, v52, v52
	v_fmac_f32_e32 v59, v53, v53
	v_fmac_f32_e32 v59, v60, v60
	v_fmac_f32_e32 v59, v61, v61
	v_fmac_f32_e32 v59, v54, v54
	v_fmac_f32_e32 v59, v55, v55
	global_store_dwordx4 v[56:57], v[42:45], off
	s_waitcnt vmcnt(15)
	v_lshlrev_b32_e32 v52, 16, v228
	v_and_b32_e32 v53, 0xffff0000, v228
	v_lshlrev_b32_e32 v46, 16, v229
	v_and_b32_e32 v47, 0xffff0000, v229
	v_lshlrev_b32_e32 v54, 16, v230
	v_and_b32_e32 v55, 0xffff0000, v230
	v_lshlrev_b32_e32 v48, 16, v231
	v_and_b32_e32 v49, 0xffff0000, v231
	v_pk_add_f32 v[38:39], v[38:39], v[52:53]
	v_pk_add_f32 v[40:41], v[40:41], v[46:47]
	v_pk_add_f32 v[46:47], v[36:37], v[48:49]
	v_pk_add_f32 v[48:49], v[34:35], v[54:55]
	v_mul_f32_e32 v34, v39, v39
	v_fmac_f32_e32 v34, v38, v38
	v_fmac_f32_e32 v34, v40, v40
	v_fmac_f32_e32 v34, v41, v41
	v_fmac_f32_e32 v34, v48, v48
	v_fmac_f32_e32 v34, v49, v49
	v_fmac_f32_e32 v34, v46, v46
	v_fmac_f32_e32 v34, v47, v47
	v_add_f32_e32 v34, v59, v34
	ds_bpermute_b32 v35, v122, v34
	v_cvt_pk_bf16_f32 v36, v38, v39
	v_cvt_pk_bf16_f32 v37, v40, v41
	v_cvt_pk_bf16_f32 v38, v48, v49
	v_cvt_pk_bf16_f32 v39, v46, v47
	s_waitcnt lgkmcnt(0)
	v_add_f32_e32 v34, v34, v35
	ds_bpermute_b32 v35, v116, v34
	global_store_dwordx4 v[56:57], v[36:39], off offset:256
	s_and_saveexec_b64 s[24:25], s[2:3]
	s_cbranch_execz .LBB0_1849
	v_lshl_add_u64 v[36:37], v[50:51], 2, s[10:11]
	s_waitcnt lgkmcnt(0)
	v_add_f32_e32 v34, v34, v35
	global_atomic_add_f32 v[36:37], v34, off
.LBB0_1849:
	s_or_b64 exec, exec, s[24:25]
	v_add_u32_e32 v34, 0xa0, v148
	s_waitcnt lgkmcnt(0)
	v_ashrrev_i32_e32 v35, 31, v34
	v_lshlrev_b64 v[36:37], 11, v[34:35]
	v_lshl_add_u64 v[36:37], s[92:93], 0, v[36:37]
	v_lshl_add_u64 v[40:41], v[146:147], 1, v[36:37]
	s_nop 0
	s_waitcnt vmcnt(15)
	v_lshlrev_b32_e32 v42, 16, v232
	v_and_b32_e32 v43, 0xffff0000, v232
	v_lshlrev_b32_e32 v36, 16, v233
	v_and_b32_e32 v37, 0xffff0000, v233
	v_lshlrev_b32_e32 v44, 16, v234
	v_and_b32_e32 v45, 0xffff0000, v234
	v_lshlrev_b32_e32 v38, 16, v235
	v_and_b32_e32 v39, 0xffff0000, v235
	v_pk_add_f32 v[36:37], v[32:33], v[36:37]
	v_pk_add_f32 v[42:43], v[30:31], v[42:43]
	v_pk_add_f32 v[38:39], v[28:29], v[38:39]
	v_pk_add_f32 v[44:45], v[26:27], v[44:45]
	v_cvt_pk_bf16_f32 v26, v42, v43
	v_cvt_pk_bf16_f32 v27, v36, v37
	v_mul_f32_e32 v43, v43, v43
	v_cvt_pk_bf16_f32 v28, v44, v45
	v_cvt_pk_bf16_f32 v29, v38, v39
	s_nop 0
	v_fmac_f32_e32 v43, v42, v42
	v_fmac_f32_e32 v43, v36, v36
	v_fmac_f32_e32 v43, v37, v37
	v_fmac_f32_e32 v43, v44, v44
	v_fmac_f32_e32 v43, v45, v45
	v_fmac_f32_e32 v43, v38, v38
	v_fmac_f32_e32 v43, v39, v39
	global_store_dwordx4 v[40:41], v[26:29], off
	s_waitcnt vmcnt(15)
	v_lshlrev_b32_e32 v36, 16, v236
	v_and_b32_e32 v37, 0xffff0000, v236
	v_lshlrev_b32_e32 v30, 16, v237
	v_and_b32_e32 v31, 0xffff0000, v237
	v_lshlrev_b32_e32 v38, 16, v238
	v_and_b32_e32 v39, 0xffff0000, v238
	v_lshlrev_b32_e32 v32, 16, v239
	v_and_b32_e32 v33, 0xffff0000, v239
	v_pk_add_f32 v[22:23], v[22:23], v[36:37]
	v_pk_add_f32 v[24:25], v[24:25], v[30:31]
	v_pk_add_f32 v[30:31], v[20:21], v[32:33]
	v_pk_add_f32 v[32:33], v[18:19], v[38:39]
	v_mul_f32_e32 v18, v23, v23
	v_fmac_f32_e32 v18, v22, v22
	v_fmac_f32_e32 v18, v24, v24
	v_fmac_f32_e32 v18, v25, v25
	v_fmac_f32_e32 v18, v32, v32
	v_fmac_f32_e32 v18, v33, v33
	v_fmac_f32_e32 v18, v30, v30
	v_fmac_f32_e32 v18, v31, v31
	v_add_f32_e32 v18, v43, v18
	ds_bpermute_b32 v19, v122, v18
	v_cvt_pk_bf16_f32 v20, v22, v23
	v_cvt_pk_bf16_f32 v21, v24, v25
	v_cvt_pk_bf16_f32 v22, v32, v33
	v_cvt_pk_bf16_f32 v23, v30, v31
	s_waitcnt lgkmcnt(0)
	v_add_f32_e32 v18, v18, v19
	ds_bpermute_b32 v19, v116, v18
	global_store_dwordx4 v[40:41], v[20:23], off offset:256
	s_and_saveexec_b64 s[24:25], s[2:3]
	s_cbranch_execz .LBB0_1851
	v_lshl_add_u64 v[20:21], v[34:35], 2, s[10:11]
	s_waitcnt lgkmcnt(0)
	v_add_f32_e32 v18, v18, v19
	global_atomic_add_f32 v[20:21], v18, off
.LBB0_1851:
	s_or_b64 exec, exec, s[24:25]
	v_add_u32_e32 v18, 0xb0, v148
	s_waitcnt lgkmcnt(0)
	v_ashrrev_i32_e32 v19, 31, v18
	v_lshlrev_b64 v[20:21], 11, v[18:19]
	v_lshl_add_u64 v[20:21], s[92:93], 0, v[20:21]
	v_lshl_add_u64 v[24:25], v[146:147], 1, v[20:21]
	s_nop 0
	s_waitcnt vmcnt(15)
	v_lshlrev_b32_e32 v26, 16, v240
	v_and_b32_e32 v27, 0xffff0000, v240
	v_lshlrev_b32_e32 v20, 16, v241
	v_and_b32_e32 v21, 0xffff0000, v241
	v_lshlrev_b32_e32 v28, 16, v242
	v_and_b32_e32 v29, 0xffff0000, v242
	v_lshlrev_b32_e32 v22, 16, v243
	v_and_b32_e32 v23, 0xffff0000, v243
	v_pk_add_f32 v[20:21], v[16:17], v[20:21]
	v_pk_add_f32 v[26:27], v[14:15], v[26:27]
	v_pk_add_f32 v[22:23], v[12:13], v[22:23]
	v_pk_add_f32 v[28:29], v[10:11], v[28:29]
	v_cvt_pk_bf16_f32 v10, v26, v27
	v_cvt_pk_bf16_f32 v11, v20, v21
	v_mul_f32_e32 v27, v27, v27
	v_cvt_pk_bf16_f32 v12, v28, v29
	v_cvt_pk_bf16_f32 v13, v22, v23
	s_nop 0
	v_fmac_f32_e32 v27, v26, v26
	v_fmac_f32_e32 v27, v20, v20
	v_fmac_f32_e32 v27, v21, v21
	v_fmac_f32_e32 v27, v28, v28
	v_fmac_f32_e32 v27, v29, v29
	v_fmac_f32_e32 v27, v22, v22
	v_fmac_f32_e32 v27, v23, v23
	global_store_dwordx4 v[24:25], v[10:13], off
	s_waitcnt vmcnt(15)
	v_lshlrev_b32_e32 v20, 16, v248
	v_and_b32_e32 v21, 0xffff0000, v248
	v_lshlrev_b32_e32 v14, 16, v249
	v_and_b32_e32 v15, 0xffff0000, v249
	v_lshlrev_b32_e32 v22, 16, v250
	v_and_b32_e32 v23, 0xffff0000, v250
	v_lshlrev_b32_e32 v16, 16, v251
	v_and_b32_e32 v17, 0xffff0000, v251
	v_pk_add_f32 v[6:7], v[6:7], v[20:21]
	v_pk_add_f32 v[8:9], v[8:9], v[14:15]
	v_pk_add_f32 v[14:15], v[4:5], v[16:17]
	v_pk_add_f32 v[16:17], v[2:3], v[22:23]
	v_mul_f32_e32 v2, v7, v7
	v_fmac_f32_e32 v2, v6, v6
	v_fmac_f32_e32 v2, v8, v8
	v_fmac_f32_e32 v2, v9, v9
	v_fmac_f32_e32 v2, v16, v16
	v_fmac_f32_e32 v2, v17, v17
	v_fmac_f32_e32 v2, v14, v14
	v_fmac_f32_e32 v2, v15, v15
	v_add_f32_e32 v2, v27, v2
	ds_bpermute_b32 v3, v122, v2
	v_cvt_pk_bf16_f32 v4, v6, v7
	v_cvt_pk_bf16_f32 v5, v8, v9
	v_cvt_pk_bf16_f32 v6, v16, v17
	v_cvt_pk_bf16_f32 v7, v14, v15
	s_waitcnt lgkmcnt(0)
	v_add_f32_e32 v2, v2, v3
	ds_bpermute_b32 v3, v116, v2
	global_store_dwordx4 v[24:25], v[4:7], off offset:256
	s_and_saveexec_b64 s[24:25], s[2:3]
	s_cbranch_execz .LBB0_1853
	v_lshl_add_u64 v[4:5], v[18:19], 2, s[10:11]
	s_waitcnt lgkmcnt(0)
	v_add_f32_e32 v2, v2, v3
	global_atomic_add_f32 v[4:5], v2, off

	.amdhsa_kernel _Z8yoco_fwd5KArgs
		.amdhsa_group_segment_fixed_size 0
		.amdhsa_private_segment_fixed_size 0
		.amdhsa_kernarg_size 488
		.amdhsa_user_sgpr_count 2
		.amdhsa_user_sgpr_dispatch_ptr 0
		.amdhsa_user_sgpr_queue_ptr 0
		.amdhsa_user_sgpr_kernarg_segment_ptr 1
		.amdhsa_user_sgpr_dispatch_id 0
		.amdhsa_user_sgpr_kernarg_preload_length 0
		.amdhsa_user_sgpr_kernarg_preload_offset 0
		.amdhsa_user_sgpr_private_segment_size 0
		.amdhsa_uses_dynamic_stack 0
		.amdhsa_enable_private_segment 0
		.amdhsa_system_sgpr_workgroup_id_x 1
		.amdhsa_system_sgpr_workgroup_id_y 0
		.amdhsa_system_sgpr_workgroup_id_z 0
		.amdhsa_system_sgpr_workgroup_info 0
		.amdhsa_system_vgpr_workitem_id 2
		.amdhsa_next_free_vgpr 256
		.amdhsa_next_free_sgpr 98
		.amdhsa_accum_offset 256
		.amdhsa_reserve_vcc 1
		.amdhsa_float_round_mode_32 0
		.amdhsa_float_round_mode_16_64 0
		.amdhsa_float_denorm_mode_32 3
		.amdhsa_float_denorm_mode_16_64 3
		.amdhsa_dx10_clamp 1
		.amdhsa_ieee_mode 1
		.amdhsa_fp16_overflow 0
		.amdhsa_tg_split 0
		.amdhsa_exception_fp_ieee_invalid_op 0
		.amdhsa_exception_fp_denorm_src 0
		.amdhsa_exception_fp_ieee_div_zero 0
		.amdhsa_exception_fp_ieee_overflow 0
		.amdhsa_exception_fp_ieee_underflow 0
		.amdhsa_exception_fp_ieee_inexact 0
		.amdhsa_exception_int_div_zero 0
	.end_amdhsa_kernel

amdhsa.kernels:
  - .agpr_count:     0
    .args:
      - .offset:         0
        .size:           232
        .value_kind:     by_value
      - .offset:         232
        .size:           4
        .value_kind:     hidden_block_count_x
      - .offset:         236
        .size:           4
        .value_kind:     hidden_block_count_y
      - .offset:         240
        .size:           4
        .value_kind:     hidden_block_count_z
      - .offset:         244
        .size:           2
        .value_kind:     hidden_group_size_x
      - .offset:         246
        .size:           2
        .value_kind:     hidden_group_size_y
      - .offset:         248
        .size:           2
        .value_kind:     hidden_group_size_z
      - .offset:         250
        .size:           2
        .value_kind:     hidden_remainder_x
      - .offset:         252
        .size:           2
        .value_kind:     hidden_remainder_y
      - .offset:         254
        .size:           2
        .value_kind:     hidden_remainder_z
      - .offset:         272
        .size:           8
        .value_kind:     hidden_global_offset_x
      - .offset:         280
        .size:           8
        .value_kind:     hidden_global_offset_y
      - .offset:         288
        .size:           8
        .value_kind:     hidden_global_offset_z
      - .offset:         296
        .size:           2
        .value_kind:     hidden_grid_dims
      - .offset:         320
        .size:           8
        .value_kind:     hidden_multigrid_sync_arg
      - .offset:         352
        .size:           4
        .value_kind:     hidden_dynamic_lds_size
    .group_segment_fixed_size: 0
    .kernarg_segment_align: 8
    .kernarg_segment_size: 488
    .language:       OpenCL C
    .language_version:
      - 2
      - 0
    .max_flat_workgroup_size: 512
    .name:           _Z8yoco_fwd5KArgs
    .private_segment_fixed_size: 0
    .sgpr_count:     104
    .sgpr_spill_count: 57
    .symbol:         _Z8yoco_fwd5KArgs.kd
    .uniform_work_group_size: 1
    .uses_dynamic_stack: false
    .vgpr_count:     256
    .vgpr_spill_count: 0
    .wavefront_size: 64
